# K-loop GLDS remapped to full 128B lines per row (new LDS image with XOR-chunk swizzle, first/last tiles keep old format)
# baseline (speedup 1.0000x reference)
; #define WAIT_V0() asm volatile("s_waitcnt vmcnt(0)" ::: "memory")
; #define SBAR() __builtin_amdgcn_sched_barrier(0)
;     ...
;   GLDS_STAGE(0, 0); WAIT_V0(); __syncthreads();
;   for (int t = 0; t < nt; ++t) {
;     const int cur = t & 1;
;     if (t + 1 < nt) GLDS_STAGE(cur ^ 1, t + 1);
; #pragma unroll
;     for (int ks = 0; ks < KS; ++ks) {
;       bf16x8 At[8], Bf[NB];
; #pragma unroll
;       for (int m = 0; m < 8; ++m) At[m] = *(const bf16x8*)(SA(cur) + lds_byte<KS>(wr * 128 + m * 16 + fr, ks * 32 + fq * 8));
; #pragma unroll
;       for (int n = 0; n < NB; ++n) Bf[n] = *(const bf16x8*)(SB(cur) + lds_byte<KS>(wc * (16 * NB) + n * 16 + fr, ks * 32 + fq * 8));
; #pragma unroll
;       for (int m = 0; m < 8; ++m)
; #pragma unroll
;         for (int n = 0; n < NB; ++n) acc[m][n] = __builtin_amdgcn_mfma_f32_16x16x32_bf16(Bf[n], At[m], acc[m][n], 0, 0, 0);
;       if (xmma) {
;         const bf16x8 Ax = *(const bf16x8*)(SA(cur) + lds_byte<KS>(256 + fr, ks * 32 + fq * 8));
; #pragma unroll
;         for (int n = 0; n < NB; ++n) accx[n] = __builtin_amdgcn_mfma_f32_16x16x32_bf16(Bf[n], Ax, accx[n], 0, 0, 0);
;       }
;       SBAR();
.LBB0_236:
	s_and_b32 s23, s22, 1
	s_xor_b32 s54, s23, 1
	s_mul_i32 s54, s54, 0x10800
	s_mul_i32 s23, s23, 0x10800
	v_mbcnt_lo_u32_b32 v220, -1, 0
	v_mbcnt_hi_u32_b32 v220, -1, v220
	v_and_b32_e32 v192, 15, v220
	v_lshrrev_b32_e32 v193, 4, v220
	v_bfe_u32 v194, v220, 1, 3
	v_xor_b32_e32 v193, v193, v194
	v_lshlrev_b32_e32 v193, 4, v193
	v_lshl_add_u32 v192, v192, 7, v193
	v_and_b32_e32 v193, 64, v192
	v_lshlrev_b32_e32 v193, 1, v193
	v_sub_u32_e32 v193, 64, v193
	s_cmp_eq_u32 s74, 0
	s_cselect_b64 s[100:101], -1, 0
	v_mov_b32_e32 v194, 0x400
	v_cndmask_b32_e64 v192, v192, v229, s[100:101]
	v_cndmask_b32_e64 v193, v193, v194, s[100:101]
	v_or_b32_e32 v128, s23, v192
	v_add_u32_e32 v223, v128, v191
	v_add_u32_e32 v227, v128, v190
	v_add_u32_e32 v234, v223, v193
	v_add_u32_e32 v231, v227, v193
	v_readfirstlane_b32 s100, v180
	ds_read_b128 v[146:149], v223 offset:34816
	ds_read_b128 v[208:211], v227
	ds_read_b128 v[150:153], v223 offset:36864
	ds_read_b128 v[154:157], v223 offset:38912
	ds_read_b128 v[158:161], v223 offset:40960
	ds_read_b128 v[212:215], v227 offset:2048
	s_add_i32 s100, s100, s54
	v_bfe_u32 v196, v180, 10, 1
	v_lshrrev_b32_e32 v197, 3, v220
	v_lshrrev_b32_e32 v198, 2, v220
	v_lshl_add_u32 v197, v196, 3, v197
	v_sub_u32_e32 v200, v197, v198
	v_lshrrev_b32_e32 v197, 4, v220
	v_lshl_add_u32 v197, v196, 2, v197
	v_and_b32_e32 v198, 7, v220
	v_xor_b32_e32 v197, v197, v198
	v_lshlrev_b32_e32 v197, 4, v197
	v_and_b32_e32 v198, 3, v220
	v_lshlrev_b32_e32 v198, 4, v198
	v_bfe_u32 v199, v220, 5, 1
	v_lshlrev_b32_e32 v199, 5, v199
	v_xor_b32_e32 v198, v198, v199
	v_lshl_add_u32 v198, v196, 6, v198
	v_sub_u32_e32 v197, v197, v198
	v_lshl_add_u32 v250, v200, 11, v197
	v_lshl_add_u32 v252, v200, 11, v197
	s_cmp_eq_u32 s74, 0x700
	s_cselect_b32 s101, 0, -1
	v_and_b32_e32 v250, s101, v250
	v_and_b32_e32 v252, s101, v252
	v_ashrrev_i32_e32 v251, 31, v250
	v_ashrrev_i32_e32 v253, 31, v252
	s_waitcnt lgkmcnt(1)
	v_mfma_f32_16x16x32_bf16 v[142:145], v[146:149], v[208:211], v[142:145]
	v_mfma_f32_16x16x32_bf16 v[138:141], v[150:153], v[208:211], v[138:141]
	v_mfma_f32_16x16x32_bf16 v[134:137], v[154:157], v[208:211], v[134:137]
	v_mfma_f32_16x16x32_bf16 v[130:133], v[158:161], v[208:211], v[130:133]
	ds_read_b128 v[216:219], v227 offset:4096
	s_mov_b32 m0, s100
	v_lshl_add_u64 v[220:221], v[162:163], 0, s[74:75]
	v_lshl_add_u64 v[220:221], v[220:221], 0, v[250:251]
	global_load_lds_dwordx4 v[220:221], off
	s_waitcnt lgkmcnt(1)
	v_mfma_f32_16x16x32_bf16 v[124:127], v[146:149], v[212:215], v[124:127]
	v_mfma_f32_16x16x32_bf16 v[120:123], v[150:153], v[212:215], v[120:123]
	v_mfma_f32_16x16x32_bf16 v[116:119], v[154:157], v[212:215], v[116:119]
	v_mfma_f32_16x16x32_bf16 v[92:95], v[158:161], v[212:215], v[92:95]
	ds_read_b128 v[208:211], v227 offset:6144
	s_add_i32 m0, s100, 0x8800
	v_lshl_add_u64 v[220:221], v[170:171], 0, s[74:75]
	v_lshl_add_u64 v[220:221], v[220:221], 0, v[252:253]
	global_load_lds_dwordx4 v[220:221], off
	s_waitcnt lgkmcnt(1)
	v_mfma_f32_16x16x32_bf16 v[60:63], v[146:149], v[216:219], v[60:63]
	v_mfma_f32_16x16x32_bf16 v[40:43], v[150:153], v[216:219], v[40:43]
	v_mfma_f32_16x16x32_bf16 v[36:39], v[154:157], v[216:219], v[36:39]
	v_mfma_f32_16x16x32_bf16 v[32:35], v[158:161], v[216:219], v[32:35]
	ds_read_b128 v[212:215], v227 offset:8192
	s_add_i32 m0, s100, 0x2000
	v_lshl_add_u64 v[220:221], v[164:165], 0, s[74:75]
	v_lshl_add_u64 v[220:221], v[220:221], 0, v[250:251]
	global_load_lds_dwordx4 v[220:221], off
	s_waitcnt lgkmcnt(1)
	v_mfma_f32_16x16x32_bf16 v[28:31], v[146:149], v[208:211], v[28:31]
	v_mfma_f32_16x16x32_bf16 v[24:27], v[150:153], v[208:211], v[24:27]
	v_mfma_f32_16x16x32_bf16 v[20:23], v[154:157], v[208:211], v[20:23]
	v_mfma_f32_16x16x32_bf16 v[16:19], v[158:161], v[208:211], v[16:19]
	ds_read_b128 v[216:219], v227 offset:10240
	s_add_i32 m0, s100, 0xa800
	v_lshl_add_u64 v[220:221], v[172:173], 0, s[74:75]
	v_lshl_add_u64 v[220:221], v[220:221], 0, v[252:253]
	global_load_lds_dwordx4 v[220:221], off
	s_waitcnt lgkmcnt(1)
	v_mfma_f32_16x16x32_bf16 v[84:87], v[146:149], v[212:215], v[84:87]
	v_mfma_f32_16x16x32_bf16 v[100:103], v[150:153], v[212:215], v[100:103]
	v_mfma_f32_16x16x32_bf16 v[108:111], v[154:157], v[212:215], v[108:111]
	v_mfma_f32_16x16x32_bf16 v[48:51], v[158:161], v[212:215], v[48:51]
	ds_read_b128 v[192:195], v234 offset:34816
	ds_read_b128 v[208:211], v227 offset:12288
	s_add_i32 m0, s100, 0x4000
	v_lshl_add_u64 v[220:221], v[166:167], 0, s[74:75]
	v_lshl_add_u64 v[220:221], v[220:221], 0, v[250:251]
	global_load_lds_dwordx4 v[220:221], off
	s_waitcnt lgkmcnt(2)
	v_mfma_f32_16x16x32_bf16 v[44:47], v[146:149], v[216:219], v[44:47]
	v_mfma_f32_16x16x32_bf16 v[64:67], v[150:153], v[216:219], v[64:67]
	v_mfma_f32_16x16x32_bf16 v[72:75], v[154:157], v[216:219], v[72:75]
	v_mfma_f32_16x16x32_bf16 v[76:79], v[158:161], v[216:219], v[76:79]
	ds_read_b128 v[196:199], v234 offset:36864
	ds_read_b128 v[212:215], v227 offset:14336
	s_add_i32 m0, s100, 0xc800
	v_lshl_add_u64 v[220:221], v[174:175], 0, s[74:75]
	v_lshl_add_u64 v[220:221], v[220:221], 0, v[252:253]
	global_load_lds_dwordx4 v[220:221], off
	s_waitcnt lgkmcnt(2)
	v_mfma_f32_16x16x32_bf16 v[96:99], v[146:149], v[208:211], v[96:99]
	v_mfma_f32_16x16x32_bf16 v[104:107], v[150:153], v[208:211], v[104:107]
	v_mfma_f32_16x16x32_bf16 v[112:115], v[154:157], v[208:211], v[112:115]
	v_mfma_f32_16x16x32_bf16 v[56:59], v[158:161], v[208:211], v[56:59]
	ds_read_b128 v[200:203], v234 offset:38912
	ds_read_b128 v[216:219], v231
	s_add_i32 m0, s100, 0x6000
	v_lshl_add_u64 v[220:221], v[168:169], 0, s[74:75]
	v_lshl_add_u64 v[220:221], v[220:221], 0, v[250:251]
	global_load_lds_dwordx4 v[220:221], off
	s_waitcnt lgkmcnt(2)
	v_mfma_f32_16x16x32_bf16 v[52:55], v[146:149], v[212:215], v[52:55]
	v_mfma_f32_16x16x32_bf16 v[68:71], v[150:153], v[212:215], v[68:71]
	v_mfma_f32_16x16x32_bf16 v[80:83], v[154:157], v[212:215], v[80:83]
	v_mfma_f32_16x16x32_bf16 v[88:91], v[158:161], v[212:215], v[88:91]
	ds_read_b128 v[204:207], v234 offset:40960
	ds_read_b128 v[208:211], v231 offset:2048
	s_add_i32 m0, s100, 0xe800
	v_lshl_add_u64 v[220:221], v[176:177], 0, s[74:75]
	v_lshl_add_u64 v[220:221], v[220:221], 0, v[252:253]
	global_load_lds_dwordx4 v[220:221], off
	s_waitcnt lgkmcnt(1)
	v_mfma_f32_16x16x32_bf16 v[142:145], v[192:195], v[216:219], v[142:145]
	v_mfma_f32_16x16x32_bf16 v[138:141], v[196:199], v[216:219], v[138:141]
	v_mfma_f32_16x16x32_bf16 v[134:137], v[200:203], v[216:219], v[134:137]
	v_mfma_f32_16x16x32_bf16 v[130:133], v[204:207], v[216:219], v[130:133]
	ds_read_b128 v[212:215], v231 offset:4096
	s_and_saveexec_b64 s[20:21], s[8:9]
	s_cbranch_execz .Lgk_inproj_xl
	v_readfirstlane_b32 s101, v189
	s_add_i32 s101, s101, s54
	s_add_i32 m0, s101, 0x8000
	v_lshl_add_u64 v[220:221], v[178:179], 0, s[74:75]
	v_lshl_add_u64 v[220:221], v[220:221], 0, v[250:251]
	global_load_lds_dwordx4 v[220:221], off
; #define SBAR() __builtin_amdgcn_sched_barrier(0)
;     ...
; #pragma unroll
;       for (int m = 0; m < 8; ++m) At[m] = *(const bf16x8*)(SA(cur) + lds_byte<KS>(wr * 128 + m * 16 + fr, ks * 32 + fq * 8));
; #pragma unroll
;       for (int n = 0; n < NB; ++n) Bf[n] = *(const bf16x8*)(SB(cur) + lds_byte<KS>(wc * (16 * NB) + n * 16 + fr, ks * 32 + fq * 8));
; #pragma unroll
;       for (int m = 0; m < 8; ++m)
; #pragma unroll
;         for (int n = 0; n < NB; ++n) acc[m][n] = __builtin_amdgcn_mfma_f32_16x16x32_bf16(Bf[n], At[m], acc[m][n], 0, 0, 0);
;       if (xmma) {
;         const bf16x8 Ax = *(const bf16x8*)(SA(cur) + lds_byte<KS>(256 + fr, ks * 32 + fq * 8));
; #pragma unroll
;         for (int n = 0; n < NB; ++n) accx[n] = __builtin_amdgcn_mfma_f32_16x16x32_bf16(Bf[n], Ax, accx[n], 0, 0, 0);
;       }
;       SBAR();
.Lgk_inproj_xl:
	s_or_b64 exec, exec, s[20:21]
	s_waitcnt lgkmcnt(1)
	v_mfma_f32_16x16x32_bf16 v[124:127], v[192:195], v[208:211], v[124:127]
	v_mfma_f32_16x16x32_bf16 v[120:123], v[196:199], v[208:211], v[120:123]
	v_mfma_f32_16x16x32_bf16 v[116:119], v[200:203], v[208:211], v[116:119]
	v_mfma_f32_16x16x32_bf16 v[92:95], v[204:207], v[208:211], v[92:95]
	ds_read_b128 v[216:219], v231 offset:6144
	s_waitcnt lgkmcnt(1)
	v_mfma_f32_16x16x32_bf16 v[60:63], v[192:195], v[212:215], v[60:63]
	v_mfma_f32_16x16x32_bf16 v[40:43], v[196:199], v[212:215], v[40:43]
	v_mfma_f32_16x16x32_bf16 v[36:39], v[200:203], v[212:215], v[36:39]
	v_mfma_f32_16x16x32_bf16 v[32:35], v[204:207], v[212:215], v[32:35]
	ds_read_b128 v[208:211], v231 offset:8192
	s_waitcnt lgkmcnt(1)
	v_mfma_f32_16x16x32_bf16 v[28:31], v[192:195], v[216:219], v[28:31]
	v_mfma_f32_16x16x32_bf16 v[24:27], v[196:199], v[216:219], v[24:27]
	v_mfma_f32_16x16x32_bf16 v[20:23], v[200:203], v[216:219], v[20:23]
	v_mfma_f32_16x16x32_bf16 v[16:19], v[204:207], v[216:219], v[16:19]
	ds_read_b128 v[212:215], v231 offset:10240
	s_waitcnt lgkmcnt(1)
	v_mfma_f32_16x16x32_bf16 v[84:87], v[192:195], v[208:211], v[84:87]
	v_mfma_f32_16x16x32_bf16 v[100:103], v[196:199], v[208:211], v[100:103]
	v_mfma_f32_16x16x32_bf16 v[108:111], v[200:203], v[208:211], v[108:111]
	v_mfma_f32_16x16x32_bf16 v[48:51], v[204:207], v[208:211], v[48:51]
	ds_read_b128 v[216:219], v231 offset:12288
	s_waitcnt lgkmcnt(1)
	v_mfma_f32_16x16x32_bf16 v[44:47], v[192:195], v[212:215], v[44:47]
	v_mfma_f32_16x16x32_bf16 v[64:67], v[196:199], v[212:215], v[64:67]
	v_mfma_f32_16x16x32_bf16 v[72:75], v[200:203], v[212:215], v[72:75]
	v_mfma_f32_16x16x32_bf16 v[76:79], v[204:207], v[212:215], v[76:79]
	ds_read_b128 v[208:211], v231 offset:14336
	s_waitcnt lgkmcnt(1)
	v_mfma_f32_16x16x32_bf16 v[96:99], v[192:195], v[216:219], v[96:99]
	v_mfma_f32_16x16x32_bf16 v[104:107], v[196:199], v[216:219], v[104:107]
	v_mfma_f32_16x16x32_bf16 v[112:115], v[200:203], v[216:219], v[112:115]
	v_mfma_f32_16x16x32_bf16 v[56:59], v[204:207], v[216:219], v[56:59]
	s_waitcnt lgkmcnt(0)
	v_mfma_f32_16x16x32_bf16 v[52:55], v[192:195], v[208:211], v[52:55]
	v_mfma_f32_16x16x32_bf16 v[68:71], v[196:199], v[208:211], v[68:71]
	v_mfma_f32_16x16x32_bf16 v[80:83], v[200:203], v[208:211], v[80:83]
	v_mfma_f32_16x16x32_bf16 v[88:91], v[204:207], v[208:211], v[88:91]
	s_and_saveexec_b64 s[20:21], s[6:7]
	s_cbranch_execz .LBB0_235
	v_sub_u32_e32 v230, v227, v190
	v_sub_u32_e32 v220, v231, v190
	ds_read_b128 v[212:215], v230 offset:32768
	ds_read_b128 v[216:219], v220 offset:32768
	s_waitcnt lgkmcnt(1)
	v_mfma_f32_16x16x32_bf16 v[12:15], v[146:149], v[212:215], v[12:15]
	v_mfma_f32_16x16x32_bf16 v[4:7], v[150:153], v[212:215], v[4:7]
	v_mfma_f32_16x16x32_bf16 v[8:11], v[154:157], v[212:215], v[8:11]
	v_mfma_f32_16x16x32_bf16 v[0:3], v[158:161], v[212:215], v[0:3]
	s_waitcnt lgkmcnt(0)
	v_mfma_f32_16x16x32_bf16 v[12:15], v[192:195], v[216:219], v[12:15]
	v_mfma_f32_16x16x32_bf16 v[4:7], v[196:199], v[216:219], v[4:7]
	v_mfma_f32_16x16x32_bf16 v[8:11], v[200:203], v[216:219], v[8:11]
	v_mfma_f32_16x16x32_bf16 v[0:3], v[204:207], v[216:219], v[0:3]
	s_branch .LBB0_235

; #define WAIT_V0() asm volatile("s_waitcnt vmcnt(0)" ::: "memory")
; #define SBAR() __builtin_amdgcn_sched_barrier(0)
;     ...
;   GLDS_STAGE(0, 0); WAIT_V0(); __syncthreads();
;   for (int t = 0; t < nt; ++t) {
;     const int cur = t & 1;
;     if (t + 1 < nt) GLDS_STAGE(cur ^ 1, t + 1);
; #pragma unroll
;     for (int ks = 0; ks < KS; ++ks) {
;       bf16x8 At[8], Bf[NB];
; #pragma unroll
;       for (int m = 0; m < 8; ++m) At[m] = *(const bf16x8*)(SA(cur) + lds_byte<KS>(wr * 128 + m * 16 + fr, ks * 32 + fq * 8));
; #pragma unroll
;       for (int n = 0; n < NB; ++n) Bf[n] = *(const bf16x8*)(SB(cur) + lds_byte<KS>(wc * (16 * NB) + n * 16 + fr, ks * 32 + fq * 8));
; #pragma unroll
;       for (int m = 0; m < 8; ++m)
; #pragma unroll
;         for (int n = 0; n < NB; ++n) acc[m][n] = __builtin_amdgcn_mfma_f32_16x16x32_bf16(Bf[n], At[m], acc[m][n], 0, 0, 0);
;       if (xmma) {
;         const bf16x8 Ax = *(const bf16x8*)(SA(cur) + lds_byte<KS>(256 + fr, ks * 32 + fq * 8));
; #pragma unroll
;         for (int n = 0; n < NB; ++n) accx[n] = __builtin_amdgcn_mfma_f32_16x16x32_bf16(Bf[n], Ax, accx[n], 0, 0, 0);
;       }
;       SBAR();
.LBB0_1295:
	s_and_b32 s22, s15, 1
	s_xor_b32 s23, s22, 1
	s_mul_i32 s23, s23, 0x10800
	s_mul_i32 s22, s22, 0x10800
	v_mbcnt_lo_u32_b32 v224, -1, 0
	v_mbcnt_hi_u32_b32 v224, -1, v224
	v_and_b32_e32 v196, 15, v224
	v_lshrrev_b32_e32 v197, 4, v224
	v_bfe_u32 v198, v224, 1, 3
	v_xor_b32_e32 v197, v197, v198
	v_lshlrev_b32_e32 v197, 4, v197
	v_lshl_add_u32 v196, v196, 7, v197
	v_and_b32_e32 v197, 64, v196
	v_lshlrev_b32_e32 v197, 1, v197
	v_sub_u32_e32 v197, 64, v197
	s_cmp_eq_u32 s64, 0
	s_cselect_b64 s[100:101], -1, 0
	v_mov_b32_e32 v198, 0x400
	v_cndmask_b32_e64 v196, v196, v182, s[100:101]
	v_cndmask_b32_e64 v197, v197, v198, s[100:101]
	v_or_b32_e32 v195, s22, v196
	v_add_u32_e32 v226, v195, v194
	v_add_u32_e32 v227, v195, v193
	v_add_u32_e32 v230, v226, v197
	v_add_u32_e32 v229, v227, v197
	v_readfirstlane_b32 s100, v183
	ds_read_b128 v[146:149], v226 offset:34816
	ds_read_b128 v[212:215], v227
	ds_read_b128 v[150:153], v226 offset:36864
	ds_read_b128 v[154:157], v226 offset:38912
	ds_read_b128 v[158:161], v226 offset:40960
	ds_read_b128 v[216:219], v227 offset:2048
	s_add_i32 s100, s100, s23
	v_bfe_u32 v200, v183, 10, 1
	v_lshrrev_b32_e32 v201, 3, v224
	v_lshrrev_b32_e32 v202, 2, v224
	v_lshl_add_u32 v201, v200, 3, v201
	v_sub_u32_e32 v204, v201, v202
	v_lshrrev_b32_e32 v201, 4, v224
	v_lshl_add_u32 v201, v200, 2, v201
	v_and_b32_e32 v202, 7, v224
	v_xor_b32_e32 v201, v201, v202
	v_lshlrev_b32_e32 v201, 4, v201
	v_and_b32_e32 v202, 3, v224
	v_lshlrev_b32_e32 v202, 4, v202
	v_bfe_u32 v203, v224, 5, 1
	v_lshlrev_b32_e32 v203, 5, v203
	v_xor_b32_e32 v202, v202, v203
	v_lshl_add_u32 v202, v200, 6, v202
	v_sub_u32_e32 v201, v201, v202
	v_lshl_add_u32 v238, v204, 11, v201
	v_lshl_add_u32 v240, v204, 11, v201
	s_cmp_eq_u32 s64, 0x700
	s_cselect_b32 s101, 0, -1
	v_and_b32_e32 v238, s101, v238
	v_and_b32_e32 v240, s101, v240
	v_ashrrev_i32_e32 v239, 31, v238
	v_ashrrev_i32_e32 v241, 31, v240
	s_waitcnt lgkmcnt(1)
	v_mfma_f32_16x16x32_bf16 v[142:145], v[146:149], v[212:215], v[142:145]
	v_mfma_f32_16x16x32_bf16 v[138:141], v[150:153], v[212:215], v[138:141]
	v_mfma_f32_16x16x32_bf16 v[134:137], v[154:157], v[212:215], v[134:137]
	v_mfma_f32_16x16x32_bf16 v[130:133], v[158:161], v[212:215], v[130:133]
	ds_read_b128 v[220:223], v227 offset:4096
	s_mov_b32 m0, s100
	v_lshl_add_u64 v[224:225], v[162:163], 0, s[64:65]
	v_lshl_add_u64 v[224:225], v[224:225], 0, v[238:239]
	global_load_lds_dwordx4 v[224:225], off
	s_waitcnt lgkmcnt(1)
	v_mfma_f32_16x16x32_bf16 v[124:127], v[146:149], v[216:219], v[124:127]
	v_mfma_f32_16x16x32_bf16 v[120:123], v[150:153], v[216:219], v[120:123]
	v_mfma_f32_16x16x32_bf16 v[116:119], v[154:157], v[216:219], v[116:119]
	v_mfma_f32_16x16x32_bf16 v[112:115], v[158:161], v[216:219], v[112:115]
	ds_read_b128 v[212:215], v227 offset:6144
	s_add_i32 m0, s100, 0x8800
	v_lshl_add_u64 v[224:225], v[170:171], 0, s[64:65]
	v_lshl_add_u64 v[224:225], v[224:225], 0, v[240:241]
	global_load_lds_dwordx4 v[224:225], off
	s_waitcnt lgkmcnt(1)
	v_mfma_f32_16x16x32_bf16 v[108:111], v[146:149], v[220:223], v[108:111]
	v_mfma_f32_16x16x32_bf16 v[104:107], v[150:153], v[220:223], v[104:107]
	v_mfma_f32_16x16x32_bf16 v[100:103], v[154:157], v[220:223], v[100:103]
	v_mfma_f32_16x16x32_bf16 v[96:99], v[158:161], v[220:223], v[96:99]
	ds_read_b128 v[216:219], v227 offset:8192
	s_add_i32 m0, s100, 0x2000
	v_lshl_add_u64 v[224:225], v[164:165], 0, s[64:65]
	v_lshl_add_u64 v[224:225], v[224:225], 0, v[238:239]
	global_load_lds_dwordx4 v[224:225], off
	s_waitcnt lgkmcnt(1)
	v_mfma_f32_16x16x32_bf16 v[92:95], v[146:149], v[212:215], v[92:95]
	v_mfma_f32_16x16x32_bf16 v[88:91], v[150:153], v[212:215], v[88:91]
	v_mfma_f32_16x16x32_bf16 v[84:87], v[154:157], v[212:215], v[84:87]
	v_mfma_f32_16x16x32_bf16 v[80:83], v[158:161], v[212:215], v[80:83]
	ds_read_b128 v[220:223], v227 offset:10240
	s_add_i32 m0, s100, 0xa800
	v_lshl_add_u64 v[224:225], v[172:173], 0, s[64:65]
	v_lshl_add_u64 v[224:225], v[224:225], 0, v[240:241]
	global_load_lds_dwordx4 v[224:225], off
	s_waitcnt lgkmcnt(1)
	v_mfma_f32_16x16x32_bf16 v[76:79], v[146:149], v[216:219], v[76:79]
	v_mfma_f32_16x16x32_bf16 v[72:75], v[150:153], v[216:219], v[72:75]
	v_mfma_f32_16x16x32_bf16 v[68:71], v[154:157], v[216:219], v[68:71]
	v_mfma_f32_16x16x32_bf16 v[64:67], v[158:161], v[216:219], v[64:67]
	ds_read_b128 v[196:199], v230 offset:34816
	ds_read_b128 v[212:215], v227 offset:12288
	s_add_i32 m0, s100, 0x4000
	v_lshl_add_u64 v[224:225], v[166:167], 0, s[64:65]
	v_lshl_add_u64 v[224:225], v[224:225], 0, v[238:239]
	global_load_lds_dwordx4 v[224:225], off
	s_waitcnt lgkmcnt(2)
	v_mfma_f32_16x16x32_bf16 v[60:63], v[146:149], v[220:223], v[60:63]
	v_mfma_f32_16x16x32_bf16 v[56:59], v[150:153], v[220:223], v[56:59]
	v_mfma_f32_16x16x32_bf16 v[52:55], v[154:157], v[220:223], v[52:55]
	v_mfma_f32_16x16x32_bf16 v[48:51], v[158:161], v[220:223], v[48:51]
	ds_read_b128 v[200:203], v230 offset:36864
	ds_read_b128 v[216:219], v227 offset:14336
	s_add_i32 m0, s100, 0xc800
	v_lshl_add_u64 v[224:225], v[174:175], 0, s[64:65]
	v_lshl_add_u64 v[224:225], v[224:225], 0, v[240:241]
	global_load_lds_dwordx4 v[224:225], off
	s_waitcnt lgkmcnt(2)
	v_mfma_f32_16x16x32_bf16 v[44:47], v[146:149], v[212:215], v[44:47]
	v_mfma_f32_16x16x32_bf16 v[40:43], v[150:153], v[212:215], v[40:43]
	v_mfma_f32_16x16x32_bf16 v[36:39], v[154:157], v[212:215], v[36:39]
	v_mfma_f32_16x16x32_bf16 v[32:35], v[158:161], v[212:215], v[32:35]
	ds_read_b128 v[204:207], v230 offset:38912
	ds_read_b128 v[220:223], v229
	s_add_i32 m0, s100, 0x6000
	v_lshl_add_u64 v[224:225], v[168:169], 0, s[64:65]
	v_lshl_add_u64 v[224:225], v[224:225], 0, v[238:239]
	global_load_lds_dwordx4 v[224:225], off
	s_waitcnt lgkmcnt(2)
	v_mfma_f32_16x16x32_bf16 v[28:31], v[146:149], v[216:219], v[28:31]
	v_mfma_f32_16x16x32_bf16 v[24:27], v[150:153], v[216:219], v[24:27]
	v_mfma_f32_16x16x32_bf16 v[20:23], v[154:157], v[216:219], v[20:23]
	v_mfma_f32_16x16x32_bf16 v[16:19], v[158:161], v[216:219], v[16:19]
	ds_read_b128 v[208:211], v230 offset:40960
	ds_read_b128 v[212:215], v229 offset:2048
	s_add_i32 m0, s100, 0xe800
	v_lshl_add_u64 v[224:225], v[176:177], 0, s[64:65]
	v_lshl_add_u64 v[224:225], v[224:225], 0, v[240:241]
	global_load_lds_dwordx4 v[224:225], off
	s_waitcnt lgkmcnt(1)
	v_mfma_f32_16x16x32_bf16 v[142:145], v[196:199], v[220:223], v[142:145]
	v_mfma_f32_16x16x32_bf16 v[138:141], v[200:203], v[220:223], v[138:141]
	v_mfma_f32_16x16x32_bf16 v[134:137], v[204:207], v[220:223], v[134:137]
	v_mfma_f32_16x16x32_bf16 v[130:133], v[208:211], v[220:223], v[130:133]
	ds_read_b128 v[216:219], v229 offset:4096
	s_and_saveexec_b64 s[20:21], s[18:19]
	s_cbranch_execz .Lgk_gates_xl
	v_readfirstlane_b32 s101, v192
	s_add_i32 s101, s101, s23
	s_add_i32 m0, s101, 0x8000
	v_lshl_add_u64 v[224:225], v[178:179], 0, s[64:65]
	v_lshl_add_u64 v[224:225], v[224:225], 0, v[238:239]
	global_load_lds_dwordx4 v[224:225], off
; #define SBAR() __builtin_amdgcn_sched_barrier(0)
;     ...
; #pragma unroll
;       for (int m = 0; m < 8; ++m) At[m] = *(const bf16x8*)(SA(cur) + lds_byte<KS>(wr * 128 + m * 16 + fr, ks * 32 + fq * 8));
; #pragma unroll
;       for (int n = 0; n < NB; ++n) Bf[n] = *(const bf16x8*)(SB(cur) + lds_byte<KS>(wc * (16 * NB) + n * 16 + fr, ks * 32 + fq * 8));
; #pragma unroll
;       for (int m = 0; m < 8; ++m)
; #pragma unroll
;         for (int n = 0; n < NB; ++n) acc[m][n] = __builtin_amdgcn_mfma_f32_16x16x32_bf16(Bf[n], At[m], acc[m][n], 0, 0, 0);
;       if (xmma) {
;         const bf16x8 Ax = *(const bf16x8*)(SA(cur) + lds_byte<KS>(256 + fr, ks * 32 + fq * 8));
; #pragma unroll
;         for (int n = 0; n < NB; ++n) accx[n] = __builtin_amdgcn_mfma_f32_16x16x32_bf16(Bf[n], Ax, accx[n], 0, 0, 0);
;       }
;       SBAR();
.Lgk_gates_xl:
	s_or_b64 exec, exec, s[20:21]
	s_waitcnt lgkmcnt(1)
	v_mfma_f32_16x16x32_bf16 v[124:127], v[196:199], v[212:215], v[124:127]
	v_mfma_f32_16x16x32_bf16 v[120:123], v[200:203], v[212:215], v[120:123]
	v_mfma_f32_16x16x32_bf16 v[116:119], v[204:207], v[212:215], v[116:119]
	v_mfma_f32_16x16x32_bf16 v[112:115], v[208:211], v[212:215], v[112:115]
	ds_read_b128 v[220:223], v229 offset:6144
	s_waitcnt lgkmcnt(1)
	v_mfma_f32_16x16x32_bf16 v[108:111], v[196:199], v[216:219], v[108:111]
	v_mfma_f32_16x16x32_bf16 v[104:107], v[200:203], v[216:219], v[104:107]
	v_mfma_f32_16x16x32_bf16 v[100:103], v[204:207], v[216:219], v[100:103]
	v_mfma_f32_16x16x32_bf16 v[96:99], v[208:211], v[216:219], v[96:99]
	ds_read_b128 v[212:215], v229 offset:8192
	s_waitcnt lgkmcnt(1)
	v_mfma_f32_16x16x32_bf16 v[92:95], v[196:199], v[220:223], v[92:95]
	v_mfma_f32_16x16x32_bf16 v[88:91], v[200:203], v[220:223], v[88:91]
	v_mfma_f32_16x16x32_bf16 v[84:87], v[204:207], v[220:223], v[84:87]
	v_mfma_f32_16x16x32_bf16 v[80:83], v[208:211], v[220:223], v[80:83]
	ds_read_b128 v[216:219], v229 offset:10240
	s_waitcnt lgkmcnt(1)
	v_mfma_f32_16x16x32_bf16 v[76:79], v[196:199], v[212:215], v[76:79]
	v_mfma_f32_16x16x32_bf16 v[72:75], v[200:203], v[212:215], v[72:75]
	v_mfma_f32_16x16x32_bf16 v[68:71], v[204:207], v[212:215], v[68:71]
	v_mfma_f32_16x16x32_bf16 v[64:67], v[208:211], v[212:215], v[64:67]
	ds_read_b128 v[220:223], v229 offset:12288
	s_waitcnt lgkmcnt(1)
	v_mfma_f32_16x16x32_bf16 v[60:63], v[196:199], v[216:219], v[60:63]
	v_mfma_f32_16x16x32_bf16 v[56:59], v[200:203], v[216:219], v[56:59]
	v_mfma_f32_16x16x32_bf16 v[52:55], v[204:207], v[216:219], v[52:55]
	v_mfma_f32_16x16x32_bf16 v[48:51], v[208:211], v[216:219], v[48:51]
	ds_read_b128 v[212:215], v229 offset:14336
	s_waitcnt lgkmcnt(1)
	v_mfma_f32_16x16x32_bf16 v[44:47], v[196:199], v[220:223], v[44:47]
	v_mfma_f32_16x16x32_bf16 v[40:43], v[200:203], v[220:223], v[40:43]
	v_mfma_f32_16x16x32_bf16 v[36:39], v[204:207], v[220:223], v[36:39]
	v_mfma_f32_16x16x32_bf16 v[32:35], v[208:211], v[220:223], v[32:35]
	s_waitcnt lgkmcnt(0)
	v_mfma_f32_16x16x32_bf16 v[28:31], v[196:199], v[212:215], v[28:31]
	v_mfma_f32_16x16x32_bf16 v[24:27], v[200:203], v[212:215], v[24:27]
	v_mfma_f32_16x16x32_bf16 v[20:23], v[204:207], v[212:215], v[20:23]
	v_mfma_f32_16x16x32_bf16 v[16:19], v[208:211], v[212:215], v[16:19]
	s_and_saveexec_b64 s[20:21], s[0:1]
	s_cbranch_execz .LBB0_1294
	v_sub_u32_e32 v228, v227, v193
	v_sub_u32_e32 v224, v229, v193
	ds_read_b128 v[216:219], v228 offset:32768
	ds_read_b128 v[220:223], v224 offset:32768
	s_waitcnt lgkmcnt(1)
	v_mfma_f32_16x16x32_bf16 v[12:15], v[146:149], v[216:219], v[12:15]
	v_mfma_f32_16x16x32_bf16 v[8:11], v[150:153], v[216:219], v[8:11]
	v_mfma_f32_16x16x32_bf16 v[4:7], v[154:157], v[216:219], v[4:7]
	v_mfma_f32_16x16x32_bf16 v[0:3], v[158:161], v[216:219], v[0:3]
	s_waitcnt lgkmcnt(0)
	v_mfma_f32_16x16x32_bf16 v[12:15], v[196:199], v[220:223], v[12:15]
	v_mfma_f32_16x16x32_bf16 v[8:11], v[200:203], v[220:223], v[8:11]
	v_mfma_f32_16x16x32_bf16 v[4:7], v[204:207], v[220:223], v[4:7]
	v_mfma_f32_16x16x32_bf16 v[0:3], v[208:211], v[220:223], v[0:3]
	s_branch .LBB0_1294

; #define WAIT_V0() asm volatile("s_waitcnt vmcnt(0)" ::: "memory")
; #define SBAR() __builtin_amdgcn_sched_barrier(0)
;     ...
;   GLDS_STAGE(0, 0); WAIT_V0(); __syncthreads();
;   for (int t = 0; t < nt; ++t) {
;     const int cur = t & 1;
;     if (t + 1 < nt) GLDS_STAGE(cur ^ 1, t + 1);
; #pragma unroll
;     for (int ks = 0; ks < KS; ++ks) {
;       bf16x8 At[8], Bf[NB];
; #pragma unroll
;       for (int m = 0; m < 8; ++m) At[m] = *(const bf16x8*)(SA(cur) + lds_byte<KS>(wr * 128 + m * 16 + fr, ks * 32 + fq * 8));
; #pragma unroll
;       for (int n = 0; n < NB; ++n) Bf[n] = *(const bf16x8*)(SB(cur) + lds_byte<KS>(wc * (16 * NB) + n * 16 + fr, ks * 32 + fq * 8));
; #pragma unroll
;       for (int m = 0; m < 8; ++m)
; #pragma unroll
;         for (int n = 0; n < NB; ++n) acc[m][n] = __builtin_amdgcn_mfma_f32_16x16x32_bf16(Bf[n], At[m], acc[m][n], 0, 0, 0);
;       if (xmma) {
;         const bf16x8 Ax = *(const bf16x8*)(SA(cur) + lds_byte<KS>(256 + fr, ks * 32 + fq * 8));
; #pragma unroll
;         for (int n = 0; n < NB; ++n) accx[n] = __builtin_amdgcn_mfma_f32_16x16x32_bf16(Bf[n], Ax, accx[n], 0, 0, 0);
;       }
;       SBAR();
.LBB0_1350:
	s_and_b32 s7, s3, 1
	s_xor_b32 s22, s7, 1
	s_mul_i32 s22, s22, 0x10800
	s_mul_i32 s7, s7, 0x10800
	v_mbcnt_lo_u32_b32 v238, -1, 0
	v_mbcnt_hi_u32_b32 v238, -1, v238
	v_and_b32_e32 v204, 15, v238
	v_lshrrev_b32_e32 v205, 4, v238
	v_bfe_u32 v206, v238, 1, 3
	v_xor_b32_e32 v205, v205, v206
	v_lshlrev_b32_e32 v205, 4, v205
	v_lshl_add_u32 v204, v204, 7, v205
	v_and_b32_e32 v205, 64, v204
	v_lshlrev_b32_e32 v205, 1, v205
	v_sub_u32_e32 v205, 64, v205
	s_cmp_eq_u32 s70, 0
	s_cselect_b64 s[100:101], -1, 0
	v_mov_b32_e32 v206, 0x400
	v_cndmask_b32_e64 v204, v204, v191, s[100:101]
	v_cndmask_b32_e64 v205, v205, v206, s[100:101]
	v_or_b32_e32 v128, s7, v204
	v_add_u32_e32 v234, v128, v203
	v_add_u32_e32 v240, v128, v202
	v_add_u32_e32 v243, v234, v205
	v_add_u32_e32 v242, v240, v205
	v_readfirstlane_b32 s100, v192
	ds_read_b128 v[146:149], v234 offset:34816
	ds_read_b128 v[220:223], v240
	ds_read_b128 v[150:153], v234 offset:36864
	ds_read_b128 v[154:157], v234 offset:38912
	ds_read_b128 v[158:161], v234 offset:40960
	ds_read_b128 v[224:227], v240 offset:2048
	s_add_i32 s100, s100, s22
	v_bfe_u32 v208, v192, 10, 1
	v_lshrrev_b32_e32 v209, 3, v238
	v_lshrrev_b32_e32 v210, 2, v238
	v_lshl_add_u32 v209, v208, 3, v209
	v_sub_u32_e32 v212, v209, v210
	v_lshrrev_b32_e32 v209, 4, v238
	v_lshl_add_u32 v209, v208, 2, v209
	v_and_b32_e32 v210, 7, v238
	v_xor_b32_e32 v209, v209, v210
	v_lshlrev_b32_e32 v209, 4, v209
	v_and_b32_e32 v210, 3, v238
	v_lshlrev_b32_e32 v210, 4, v210
	v_bfe_u32 v211, v238, 5, 1
	v_lshlrev_b32_e32 v211, 5, v211
	v_xor_b32_e32 v210, v210, v211
	v_lshl_add_u32 v210, v208, 6, v210
	v_sub_u32_e32 v209, v209, v210
	v_lshl_add_u32 v244, v212, 11, v209
	v_lshl_add_u32 v246, v212, 11, v209
	s_cmp_eq_u32 s70, 0x700
	s_cselect_b32 s101, 0, -1
	v_and_b32_e32 v244, s101, v244
	v_and_b32_e32 v246, s101, v246
	v_ashrrev_i32_e32 v245, 31, v244
	v_ashrrev_i32_e32 v247, 31, v246
	s_waitcnt lgkmcnt(1)
	v_mfma_f32_16x16x32_bf16 v[142:145], v[146:149], v[220:223], v[142:145]
	v_mfma_f32_16x16x32_bf16 v[138:141], v[150:153], v[220:223], v[138:141]
	v_mfma_f32_16x16x32_bf16 v[134:137], v[154:157], v[220:223], v[134:137]
	v_mfma_f32_16x16x32_bf16 v[130:133], v[158:161], v[220:223], v[130:133]
	ds_read_b128 v[228:231], v240 offset:4096
	s_mov_b32 m0, s100
	v_lshl_add_u64 v[238:239], v[162:163], 0, s[70:71]
	v_lshl_add_u64 v[238:239], v[238:239], 0, v[244:245]
	global_load_lds_dwordx4 v[238:239], off
	s_waitcnt lgkmcnt(1)
	v_mfma_f32_16x16x32_bf16 v[124:127], v[146:149], v[224:227], v[124:127]
	v_mfma_f32_16x16x32_bf16 v[120:123], v[150:153], v[224:227], v[120:123]
	v_mfma_f32_16x16x32_bf16 v[116:119], v[154:157], v[224:227], v[116:119]
	v_mfma_f32_16x16x32_bf16 v[112:115], v[158:161], v[224:227], v[112:115]
	ds_read_b128 v[220:223], v240 offset:6144
	s_add_i32 m0, s100, 0x8800
	v_lshl_add_u64 v[238:239], v[170:171], 0, s[70:71]
	v_lshl_add_u64 v[238:239], v[238:239], 0, v[246:247]
	global_load_lds_dwordx4 v[238:239], off
	s_waitcnt lgkmcnt(1)
	v_mfma_f32_16x16x32_bf16 v[108:111], v[146:149], v[228:231], v[108:111]
	v_mfma_f32_16x16x32_bf16 v[104:107], v[150:153], v[228:231], v[104:107]
	v_mfma_f32_16x16x32_bf16 v[100:103], v[154:157], v[228:231], v[100:103]
	v_mfma_f32_16x16x32_bf16 v[96:99], v[158:161], v[228:231], v[96:99]
	ds_read_b128 v[224:227], v240 offset:8192
	s_add_i32 m0, s100, 0x2000
	v_lshl_add_u64 v[238:239], v[164:165], 0, s[70:71]
	v_lshl_add_u64 v[238:239], v[238:239], 0, v[244:245]
	global_load_lds_dwordx4 v[238:239], off
	s_waitcnt lgkmcnt(1)
	v_mfma_f32_16x16x32_bf16 v[92:95], v[146:149], v[220:223], v[92:95]
	v_mfma_f32_16x16x32_bf16 v[88:91], v[150:153], v[220:223], v[88:91]
	v_mfma_f32_16x16x32_bf16 v[84:87], v[154:157], v[220:223], v[84:87]
	v_mfma_f32_16x16x32_bf16 v[80:83], v[158:161], v[220:223], v[80:83]
	ds_read_b128 v[228:231], v240 offset:10240
	s_add_i32 m0, s100, 0xa800
	v_lshl_add_u64 v[238:239], v[172:173], 0, s[70:71]
	v_lshl_add_u64 v[238:239], v[238:239], 0, v[246:247]
	global_load_lds_dwordx4 v[238:239], off
	s_waitcnt lgkmcnt(1)
	v_mfma_f32_16x16x32_bf16 v[76:79], v[146:149], v[224:227], v[76:79]
	v_mfma_f32_16x16x32_bf16 v[72:75], v[150:153], v[224:227], v[72:75]
	v_mfma_f32_16x16x32_bf16 v[68:71], v[154:157], v[224:227], v[68:71]
	v_mfma_f32_16x16x32_bf16 v[64:67], v[158:161], v[224:227], v[64:67]
	ds_read_b128 v[204:207], v243 offset:34816
	ds_read_b128 v[220:223], v240 offset:12288
	s_add_i32 m0, s100, 0x4000
	v_lshl_add_u64 v[238:239], v[166:167], 0, s[70:71]
	v_lshl_add_u64 v[238:239], v[238:239], 0, v[244:245]
	global_load_lds_dwordx4 v[238:239], off
	s_waitcnt lgkmcnt(2)
	v_mfma_f32_16x16x32_bf16 v[60:63], v[146:149], v[228:231], v[60:63]
	v_mfma_f32_16x16x32_bf16 v[56:59], v[150:153], v[228:231], v[56:59]
	v_mfma_f32_16x16x32_bf16 v[52:55], v[154:157], v[228:231], v[52:55]
	v_mfma_f32_16x16x32_bf16 v[48:51], v[158:161], v[228:231], v[48:51]
	ds_read_b128 v[208:211], v243 offset:36864
	ds_read_b128 v[224:227], v240 offset:14336
	s_add_i32 m0, s100, 0xc800
	v_lshl_add_u64 v[238:239], v[174:175], 0, s[70:71]
	v_lshl_add_u64 v[238:239], v[238:239], 0, v[246:247]
	global_load_lds_dwordx4 v[238:239], off
	s_waitcnt lgkmcnt(2)
	v_mfma_f32_16x16x32_bf16 v[44:47], v[146:149], v[220:223], v[44:47]
	v_mfma_f32_16x16x32_bf16 v[40:43], v[150:153], v[220:223], v[40:43]
	v_mfma_f32_16x16x32_bf16 v[36:39], v[154:157], v[220:223], v[36:39]
	v_mfma_f32_16x16x32_bf16 v[32:35], v[158:161], v[220:223], v[32:35]
	ds_read_b128 v[212:215], v243 offset:38912
	ds_read_b128 v[228:231], v242
	s_add_i32 m0, s100, 0x6000
	v_lshl_add_u64 v[238:239], v[168:169], 0, s[70:71]
	v_lshl_add_u64 v[238:239], v[238:239], 0, v[244:245]
	global_load_lds_dwordx4 v[238:239], off
	s_waitcnt lgkmcnt(2)
	v_mfma_f32_16x16x32_bf16 v[28:31], v[146:149], v[224:227], v[28:31]
	v_mfma_f32_16x16x32_bf16 v[24:27], v[150:153], v[224:227], v[24:27]
	v_mfma_f32_16x16x32_bf16 v[20:23], v[154:157], v[224:227], v[20:23]
	v_mfma_f32_16x16x32_bf16 v[16:19], v[158:161], v[224:227], v[16:19]
	ds_read_b128 v[216:219], v243 offset:40960
	ds_read_b128 v[220:223], v242 offset:2048
	s_add_i32 m0, s100, 0xe800
	v_lshl_add_u64 v[238:239], v[176:177], 0, s[70:71]
	v_lshl_add_u64 v[238:239], v[238:239], 0, v[246:247]
	global_load_lds_dwordx4 v[238:239], off
	s_waitcnt lgkmcnt(1)
	v_mfma_f32_16x16x32_bf16 v[142:145], v[204:207], v[228:231], v[142:145]
	v_mfma_f32_16x16x32_bf16 v[138:141], v[208:211], v[228:231], v[138:141]
	v_mfma_f32_16x16x32_bf16 v[134:137], v[212:215], v[228:231], v[134:137]
	v_mfma_f32_16x16x32_bf16 v[130:133], v[216:219], v[228:231], v[130:133]
	ds_read_b128 v[224:227], v242 offset:4096
	s_and_saveexec_b64 s[20:21], s[68:69]
	s_cbranch_execz .Lgk_out_xl
	v_readfirstlane_b32 s101, v201
	s_add_i32 s101, s101, s22
	s_add_i32 m0, s101, 0x8000
	v_lshl_add_u64 v[238:239], v[178:179], 0, s[70:71]
	v_lshl_add_u64 v[238:239], v[238:239], 0, v[244:245]
	global_load_lds_dwordx4 v[238:239], off
; #define SBAR() __builtin_amdgcn_sched_barrier(0)
;     ...
; #pragma unroll
;       for (int m = 0; m < 8; ++m) At[m] = *(const bf16x8*)(SA(cur) + lds_byte<KS>(wr * 128 + m * 16 + fr, ks * 32 + fq * 8));
; #pragma unroll
;       for (int n = 0; n < NB; ++n) Bf[n] = *(const bf16x8*)(SB(cur) + lds_byte<KS>(wc * (16 * NB) + n * 16 + fr, ks * 32 + fq * 8));
; #pragma unroll
;       for (int m = 0; m < 8; ++m)
; #pragma unroll
;         for (int n = 0; n < NB; ++n) acc[m][n] = __builtin_amdgcn_mfma_f32_16x16x32_bf16(Bf[n], At[m], acc[m][n], 0, 0, 0);
;       if (xmma) {
;         const bf16x8 Ax = *(const bf16x8*)(SA(cur) + lds_byte<KS>(256 + fr, ks * 32 + fq * 8));
; #pragma unroll
;         for (int n = 0; n < NB; ++n) accx[n] = __builtin_amdgcn_mfma_f32_16x16x32_bf16(Bf[n], Ax, accx[n], 0, 0, 0);
;       }
;       SBAR();
.Lgk_out_xl:
	s_or_b64 exec, exec, s[20:21]
	s_waitcnt lgkmcnt(1)
	v_mfma_f32_16x16x32_bf16 v[124:127], v[204:207], v[220:223], v[124:127]
	v_mfma_f32_16x16x32_bf16 v[120:123], v[208:211], v[220:223], v[120:123]
	v_mfma_f32_16x16x32_bf16 v[116:119], v[212:215], v[220:223], v[116:119]
	v_mfma_f32_16x16x32_bf16 v[112:115], v[216:219], v[220:223], v[112:115]
	ds_read_b128 v[228:231], v242 offset:6144
	s_waitcnt lgkmcnt(1)
	v_mfma_f32_16x16x32_bf16 v[108:111], v[204:207], v[224:227], v[108:111]
	v_mfma_f32_16x16x32_bf16 v[104:107], v[208:211], v[224:227], v[104:107]
	v_mfma_f32_16x16x32_bf16 v[100:103], v[212:215], v[224:227], v[100:103]
	v_mfma_f32_16x16x32_bf16 v[96:99], v[216:219], v[224:227], v[96:99]
	ds_read_b128 v[220:223], v242 offset:8192
	s_waitcnt lgkmcnt(1)
	v_mfma_f32_16x16x32_bf16 v[92:95], v[204:207], v[228:231], v[92:95]
	v_mfma_f32_16x16x32_bf16 v[88:91], v[208:211], v[228:231], v[88:91]
	v_mfma_f32_16x16x32_bf16 v[84:87], v[212:215], v[228:231], v[84:87]
	v_mfma_f32_16x16x32_bf16 v[80:83], v[216:219], v[228:231], v[80:83]
	ds_read_b128 v[224:227], v242 offset:10240
	s_waitcnt lgkmcnt(1)
	v_mfma_f32_16x16x32_bf16 v[76:79], v[204:207], v[220:223], v[76:79]
	v_mfma_f32_16x16x32_bf16 v[72:75], v[208:211], v[220:223], v[72:75]
	v_mfma_f32_16x16x32_bf16 v[68:71], v[212:215], v[220:223], v[68:71]
	v_mfma_f32_16x16x32_bf16 v[64:67], v[216:219], v[220:223], v[64:67]
	ds_read_b128 v[228:231], v242 offset:12288
	s_waitcnt lgkmcnt(1)
	v_mfma_f32_16x16x32_bf16 v[60:63], v[204:207], v[224:227], v[60:63]
	v_mfma_f32_16x16x32_bf16 v[56:59], v[208:211], v[224:227], v[56:59]
	v_mfma_f32_16x16x32_bf16 v[52:55], v[212:215], v[224:227], v[52:55]
	v_mfma_f32_16x16x32_bf16 v[48:51], v[216:219], v[224:227], v[48:51]
	ds_read_b128 v[220:223], v242 offset:14336
	s_waitcnt lgkmcnt(1)
	v_mfma_f32_16x16x32_bf16 v[44:47], v[204:207], v[228:231], v[44:47]
	v_mfma_f32_16x16x32_bf16 v[40:43], v[208:211], v[228:231], v[40:43]
	v_mfma_f32_16x16x32_bf16 v[36:39], v[212:215], v[228:231], v[36:39]
	v_mfma_f32_16x16x32_bf16 v[32:35], v[216:219], v[228:231], v[32:35]
	s_waitcnt lgkmcnt(0)
	v_mfma_f32_16x16x32_bf16 v[28:31], v[204:207], v[220:223], v[28:31]
	v_mfma_f32_16x16x32_bf16 v[24:27], v[208:211], v[220:223], v[24:27]
	v_mfma_f32_16x16x32_bf16 v[20:23], v[212:215], v[220:223], v[20:23]
	v_mfma_f32_16x16x32_bf16 v[16:19], v[216:219], v[220:223], v[16:19]
	s_and_saveexec_b64 s[20:21], s[4:5]
	s_cbranch_execz .LBB0_1349
	v_sub_u32_e32 v241, v240, v202
	v_sub_u32_e32 v238, v242, v202
	ds_read_b128 v[224:227], v241 offset:32768
	ds_read_b128 v[228:231], v238 offset:32768
	s_waitcnt lgkmcnt(1)
	v_mfma_f32_16x16x32_bf16 v[12:15], v[146:149], v[224:227], v[12:15]
	v_mfma_f32_16x16x32_bf16 v[8:11], v[150:153], v[224:227], v[8:11]
	v_mfma_f32_16x16x32_bf16 v[4:7], v[154:157], v[224:227], v[4:7]
	v_mfma_f32_16x16x32_bf16 v[0:3], v[158:161], v[224:227], v[0:3]
	s_waitcnt lgkmcnt(0)
	v_mfma_f32_16x16x32_bf16 v[12:15], v[204:207], v[228:231], v[12:15]
	v_mfma_f32_16x16x32_bf16 v[8:11], v[208:211], v[228:231], v[8:11]
	v_mfma_f32_16x16x32_bf16 v[4:7], v[212:215], v[228:231], v[4:7]
	v_mfma_f32_16x16x32_bf16 v[0:3], v[216:219], v[228:231], v[0:3]
	s_branch .LBB0_1349

; #define WAIT_V0() asm volatile("s_waitcnt vmcnt(0)" ::: "memory")
; #define SBAR() __builtin_amdgcn_sched_barrier(0)
;     ...
;   GLDS_STAGE(0, 0); WAIT_V0(); __syncthreads();
;   for (int t = 0; t < nt; ++t) {
;     const int cur = t & 1;
;     if (t + 1 < nt) GLDS_STAGE(cur ^ 1, t + 1);
; #pragma unroll
;     for (int ks = 0; ks < KS; ++ks) {
;       bf16x8 At[8], Bf[NB];
; #pragma unroll
;       for (int m = 0; m < 8; ++m) At[m] = *(const bf16x8*)(SA(cur) + lds_byte<KS>(wr * 128 + m * 16 + fr, ks * 32 + fq * 8));
; #pragma unroll
;       for (int n = 0; n < NB; ++n) Bf[n] = *(const bf16x8*)(SB(cur) + lds_byte<KS>(wc * (16 * NB) + n * 16 + fr, ks * 32 + fq * 8));
; #pragma unroll
;       for (int m = 0; m < 8; ++m)
; #pragma unroll
;         for (int n = 0; n < NB; ++n) acc[m][n] = __builtin_amdgcn_mfma_f32_16x16x32_bf16(Bf[n], At[m], acc[m][n], 0, 0, 0);
;       if (xmma) {
;         const bf16x8 Ax = *(const bf16x8*)(SA(cur) + lds_byte<KS>(256 + fr, ks * 32 + fq * 8));
; #pragma unroll
;         for (int n = 0; n < NB; ++n) accx[n] = __builtin_amdgcn_mfma_f32_16x16x32_bf16(Bf[n], Ax, accx[n], 0, 0, 0);
;       }
;       SBAR();
;     }
.LBB0_1744:
	s_and_b32 s5, s3, 1
	s_xor_b32 s17, s5, 1
	s_mul_i32 s17, s17, 0x10800
	s_mul_i32 s5, s5, 0x10800
	v_mbcnt_lo_u32_b32 v238, -1, 0
	v_mbcnt_hi_u32_b32 v238, -1, v238
	v_and_b32_e32 v204, 15, v238
	v_lshrrev_b32_e32 v205, 4, v238
	v_bfe_u32 v206, v238, 1, 3
	v_xor_b32_e32 v205, v205, v206
	v_lshlrev_b32_e32 v205, 4, v205
	v_lshl_add_u32 v204, v204, 7, v205
	v_and_b32_e32 v205, 64, v204
	v_lshlrev_b32_e32 v205, 1, v205
	v_sub_u32_e32 v205, 64, v205
	s_cmp_eq_u32 s66, 0
	s_cselect_b64 s[100:101], -1, 0
	v_mov_b32_e32 v206, 0x400
	v_cndmask_b32_e64 v204, v204, v191, s[100:101]
	v_cndmask_b32_e64 v205, v205, v206, s[100:101]
	v_or_b32_e32 v128, s5, v204
	v_add_u32_e32 v234, v128, v203
	v_add_u32_e32 v240, v128, v202
	v_add_u32_e32 v243, v234, v205
	v_add_u32_e32 v242, v240, v205
	v_readfirstlane_b32 s100, v192
	ds_read_b128 v[146:149], v234 offset:34816
	ds_read_b128 v[220:223], v240
	ds_read_b128 v[150:153], v234 offset:36864
	ds_read_b128 v[154:157], v234 offset:38912
	ds_read_b128 v[158:161], v234 offset:40960
	ds_read_b128 v[224:227], v240 offset:2048
	s_add_i32 s100, s100, s17
	v_bfe_u32 v208, v192, 10, 1
	v_lshrrev_b32_e32 v209, 3, v238
	v_lshrrev_b32_e32 v210, 2, v238
	v_lshl_add_u32 v209, v208, 3, v209
	v_sub_u32_e32 v212, v209, v210
	v_lshrrev_b32_e32 v209, 4, v238
	v_lshl_add_u32 v209, v208, 2, v209
	v_and_b32_e32 v210, 7, v238
	v_xor_b32_e32 v209, v209, v210
	v_lshlrev_b32_e32 v209, 4, v209
	v_and_b32_e32 v210, 3, v238
	v_lshlrev_b32_e32 v210, 4, v210
	v_bfe_u32 v211, v238, 5, 1
	v_lshlrev_b32_e32 v211, 5, v211
	v_xor_b32_e32 v210, v210, v211
	v_lshl_add_u32 v210, v208, 6, v210
	v_sub_u32_e32 v209, v209, v210
	v_lshl_add_u32 v244, v212, 13, v209
	v_lshl_add_u32 v246, v212, 13, v209
	s_cmp_eq_u32 s66, 0x1f00
	s_cselect_b32 s101, 0, -1
	v_and_b32_e32 v244, s101, v244
	v_and_b32_e32 v246, s101, v246
	v_ashrrev_i32_e32 v245, 31, v244
	v_ashrrev_i32_e32 v247, 31, v246
	s_waitcnt lgkmcnt(1)
	v_mfma_f32_16x16x32_bf16 v[142:145], v[146:149], v[220:223], v[142:145]
	v_mfma_f32_16x16x32_bf16 v[138:141], v[150:153], v[220:223], v[138:141]
	v_mfma_f32_16x16x32_bf16 v[134:137], v[154:157], v[220:223], v[134:137]
	v_mfma_f32_16x16x32_bf16 v[130:133], v[158:161], v[220:223], v[130:133]
	ds_read_b128 v[228:231], v240 offset:4096
	s_mov_b32 m0, s100
	v_lshl_add_u64 v[238:239], v[162:163], 0, s[66:67]
	v_lshl_add_u64 v[238:239], v[238:239], 0, v[244:245]
	global_load_lds_dwordx4 v[238:239], off
	s_waitcnt lgkmcnt(1)
	v_mfma_f32_16x16x32_bf16 v[124:127], v[146:149], v[224:227], v[124:127]
	v_mfma_f32_16x16x32_bf16 v[120:123], v[150:153], v[224:227], v[120:123]
	v_mfma_f32_16x16x32_bf16 v[116:119], v[154:157], v[224:227], v[116:119]
	v_mfma_f32_16x16x32_bf16 v[112:115], v[158:161], v[224:227], v[112:115]
	ds_read_b128 v[220:223], v240 offset:6144
	s_add_i32 m0, s100, 0x8800
	v_lshl_add_u64 v[238:239], v[170:171], 0, s[66:67]
	v_lshl_add_u64 v[238:239], v[238:239], 0, v[246:247]
	global_load_lds_dwordx4 v[238:239], off
	s_waitcnt lgkmcnt(1)
	v_mfma_f32_16x16x32_bf16 v[108:111], v[146:149], v[228:231], v[108:111]
	v_mfma_f32_16x16x32_bf16 v[104:107], v[150:153], v[228:231], v[104:107]
	v_mfma_f32_16x16x32_bf16 v[100:103], v[154:157], v[228:231], v[100:103]
	v_mfma_f32_16x16x32_bf16 v[96:99], v[158:161], v[228:231], v[96:99]
	ds_read_b128 v[224:227], v240 offset:8192
	s_add_i32 m0, s100, 0x2000
	v_lshl_add_u64 v[238:239], v[164:165], 0, s[66:67]
	v_lshl_add_u64 v[238:239], v[238:239], 0, v[244:245]
	global_load_lds_dwordx4 v[238:239], off
	s_waitcnt lgkmcnt(1)
	v_mfma_f32_16x16x32_bf16 v[92:95], v[146:149], v[220:223], v[92:95]
	v_mfma_f32_16x16x32_bf16 v[88:91], v[150:153], v[220:223], v[88:91]
	v_mfma_f32_16x16x32_bf16 v[84:87], v[154:157], v[220:223], v[84:87]
	v_mfma_f32_16x16x32_bf16 v[80:83], v[158:161], v[220:223], v[80:83]
	ds_read_b128 v[228:231], v240 offset:10240
	s_add_i32 m0, s100, 0xa800
	v_lshl_add_u64 v[238:239], v[172:173], 0, s[66:67]
	v_lshl_add_u64 v[238:239], v[238:239], 0, v[246:247]
	global_load_lds_dwordx4 v[238:239], off
	s_waitcnt lgkmcnt(1)
	v_mfma_f32_16x16x32_bf16 v[76:79], v[146:149], v[224:227], v[76:79]
	v_mfma_f32_16x16x32_bf16 v[72:75], v[150:153], v[224:227], v[72:75]
	v_mfma_f32_16x16x32_bf16 v[68:71], v[154:157], v[224:227], v[68:71]
	v_mfma_f32_16x16x32_bf16 v[64:67], v[158:161], v[224:227], v[64:67]
	ds_read_b128 v[204:207], v243 offset:34816
	ds_read_b128 v[220:223], v240 offset:12288
	s_add_i32 m0, s100, 0x4000
	v_lshl_add_u64 v[238:239], v[166:167], 0, s[66:67]
	v_lshl_add_u64 v[238:239], v[238:239], 0, v[244:245]
	global_load_lds_dwordx4 v[238:239], off
	s_waitcnt lgkmcnt(2)
	v_mfma_f32_16x16x32_bf16 v[60:63], v[146:149], v[228:231], v[60:63]
	v_mfma_f32_16x16x32_bf16 v[56:59], v[150:153], v[228:231], v[56:59]
	v_mfma_f32_16x16x32_bf16 v[52:55], v[154:157], v[228:231], v[52:55]
	v_mfma_f32_16x16x32_bf16 v[48:51], v[158:161], v[228:231], v[48:51]
	ds_read_b128 v[208:211], v243 offset:36864
	ds_read_b128 v[224:227], v240 offset:14336
	s_add_i32 m0, s100, 0xc800
	v_lshl_add_u64 v[238:239], v[174:175], 0, s[66:67]
	v_lshl_add_u64 v[238:239], v[238:239], 0, v[246:247]
	global_load_lds_dwordx4 v[238:239], off
	s_waitcnt lgkmcnt(2)
	v_mfma_f32_16x16x32_bf16 v[44:47], v[146:149], v[220:223], v[44:47]
	v_mfma_f32_16x16x32_bf16 v[40:43], v[150:153], v[220:223], v[40:43]
	v_mfma_f32_16x16x32_bf16 v[36:39], v[154:157], v[220:223], v[36:39]
	v_mfma_f32_16x16x32_bf16 v[32:35], v[158:161], v[220:223], v[32:35]
	ds_read_b128 v[212:215], v243 offset:38912
	ds_read_b128 v[228:231], v242
	s_add_i32 m0, s100, 0x6000
	v_lshl_add_u64 v[238:239], v[168:169], 0, s[66:67]
	v_lshl_add_u64 v[238:239], v[238:239], 0, v[244:245]
	global_load_lds_dwordx4 v[238:239], off
	s_waitcnt lgkmcnt(2)
	v_mfma_f32_16x16x32_bf16 v[28:31], v[146:149], v[224:227], v[28:31]
	v_mfma_f32_16x16x32_bf16 v[24:27], v[150:153], v[224:227], v[24:27]
	v_mfma_f32_16x16x32_bf16 v[20:23], v[154:157], v[224:227], v[20:23]
	v_mfma_f32_16x16x32_bf16 v[16:19], v[158:161], v[224:227], v[16:19]
	ds_read_b128 v[216:219], v243 offset:40960
	ds_read_b128 v[220:223], v242 offset:2048
	s_add_i32 m0, s100, 0xe800
	v_lshl_add_u64 v[238:239], v[176:177], 0, s[66:67]
	v_lshl_add_u64 v[238:239], v[238:239], 0, v[246:247]
	global_load_lds_dwordx4 v[238:239], off
	s_waitcnt lgkmcnt(1)
	v_mfma_f32_16x16x32_bf16 v[142:145], v[204:207], v[228:231], v[142:145]
	v_mfma_f32_16x16x32_bf16 v[138:141], v[208:211], v[228:231], v[138:141]
	v_mfma_f32_16x16x32_bf16 v[134:137], v[212:215], v[228:231], v[134:137]
	v_mfma_f32_16x16x32_bf16 v[130:133], v[216:219], v[228:231], v[130:133]
	ds_read_b128 v[224:227], v242 offset:4096
	s_and_saveexec_b64 s[20:21], s[64:65]
	s_cbranch_execz .Lgk_down_xl
	v_readfirstlane_b32 s101, v201
	s_add_i32 s101, s101, s17
	s_add_i32 m0, s101, 0x8000
	v_lshl_add_u64 v[238:239], v[178:179], 0, s[66:67]
	v_lshl_add_u64 v[238:239], v[238:239], 0, v[244:245]
	global_load_lds_dwordx4 v[238:239], off
;     ...
;       bf16x8 At[8], Bf[NB];
; #pragma unroll
;       for (int m = 0; m < 8; ++m) At[m] = *(const bf16x8*)(SA(cur) + lds_byte<KS>(wr * 128 + m * 16 + fr, ks * 32 + fq * 8));
; #pragma unroll
;       for (int n = 0; n < NB; ++n) Bf[n] = *(const bf16x8*)(SB(cur) + lds_byte<KS>(wc * (16 * NB) + n * 16 + fr, ks * 32 + fq * 8));
; #pragma unroll
;       for (int m = 0; m < 8; ++m)
; #pragma unroll
;         for (int n = 0; n < NB; ++n) acc[m][n] = __builtin_amdgcn_mfma_f32_16x16x32_bf16(Bf[n], At[m], acc[m][n], 0, 0, 0);
;       if (xmma) {
;         const bf16x8 Ax = *(const bf16x8*)(SA(cur) + lds_byte<KS>(256 + fr, ks * 32 + fq * 8));
; #pragma unroll
;         for (int n = 0; n < NB; ++n) accx[n] = __builtin_amdgcn_mfma_f32_16x16x32_bf16(Bf[n], Ax, accx[n], 0, 0, 0);
;       }
.Lgk_down_xl:
	s_or_b64 exec, exec, s[20:21]
	s_waitcnt lgkmcnt(1)
	v_mfma_f32_16x16x32_bf16 v[124:127], v[204:207], v[220:223], v[124:127]
	v_mfma_f32_16x16x32_bf16 v[120:123], v[208:211], v[220:223], v[120:123]
	v_mfma_f32_16x16x32_bf16 v[116:119], v[212:215], v[220:223], v[116:119]
	v_mfma_f32_16x16x32_bf16 v[112:115], v[216:219], v[220:223], v[112:115]
	ds_read_b128 v[228:231], v242 offset:6144
	s_waitcnt lgkmcnt(1)
	v_mfma_f32_16x16x32_bf16 v[108:111], v[204:207], v[224:227], v[108:111]
	v_mfma_f32_16x16x32_bf16 v[104:107], v[208:211], v[224:227], v[104:107]
	v_mfma_f32_16x16x32_bf16 v[100:103], v[212:215], v[224:227], v[100:103]
	v_mfma_f32_16x16x32_bf16 v[96:99], v[216:219], v[224:227], v[96:99]
	ds_read_b128 v[220:223], v242 offset:8192
	s_waitcnt lgkmcnt(1)
	v_mfma_f32_16x16x32_bf16 v[92:95], v[204:207], v[228:231], v[92:95]
	v_mfma_f32_16x16x32_bf16 v[88:91], v[208:211], v[228:231], v[88:91]
	v_mfma_f32_16x16x32_bf16 v[84:87], v[212:215], v[228:231], v[84:87]
	v_mfma_f32_16x16x32_bf16 v[80:83], v[216:219], v[228:231], v[80:83]
	ds_read_b128 v[224:227], v242 offset:10240
	s_waitcnt lgkmcnt(1)
	v_mfma_f32_16x16x32_bf16 v[76:79], v[204:207], v[220:223], v[76:79]
	v_mfma_f32_16x16x32_bf16 v[72:75], v[208:211], v[220:223], v[72:75]
	v_mfma_f32_16x16x32_bf16 v[68:71], v[212:215], v[220:223], v[68:71]
	v_mfma_f32_16x16x32_bf16 v[64:67], v[216:219], v[220:223], v[64:67]
	ds_read_b128 v[228:231], v242 offset:12288
	s_waitcnt lgkmcnt(1)
	v_mfma_f32_16x16x32_bf16 v[60:63], v[204:207], v[224:227], v[60:63]
	v_mfma_f32_16x16x32_bf16 v[56:59], v[208:211], v[224:227], v[56:59]
	v_mfma_f32_16x16x32_bf16 v[52:55], v[212:215], v[224:227], v[52:55]
	v_mfma_f32_16x16x32_bf16 v[48:51], v[216:219], v[224:227], v[48:51]
	ds_read_b128 v[220:223], v242 offset:14336
	s_waitcnt lgkmcnt(1)
	v_mfma_f32_16x16x32_bf16 v[44:47], v[204:207], v[228:231], v[44:47]
	v_mfma_f32_16x16x32_bf16 v[40:43], v[208:211], v[228:231], v[40:43]
	v_mfma_f32_16x16x32_bf16 v[36:39], v[212:215], v[228:231], v[36:39]
	v_mfma_f32_16x16x32_bf16 v[32:35], v[216:219], v[228:231], v[32:35]
	s_waitcnt lgkmcnt(0)
	v_mfma_f32_16x16x32_bf16 v[28:31], v[204:207], v[220:223], v[28:31]
	v_mfma_f32_16x16x32_bf16 v[24:27], v[208:211], v[220:223], v[24:27]
	v_mfma_f32_16x16x32_bf16 v[20:23], v[212:215], v[220:223], v[20:23]
	v_mfma_f32_16x16x32_bf16 v[16:19], v[216:219], v[220:223], v[16:19]
	s_and_saveexec_b64 s[20:21], s[62:63]
	s_cbranch_execz .LBB0_1743
	v_sub_u32_e32 v241, v240, v202
	v_sub_u32_e32 v238, v242, v202
	ds_read_b128 v[224:227], v241 offset:32768
	ds_read_b128 v[228:231], v238 offset:32768
	s_waitcnt lgkmcnt(1)
	v_mfma_f32_16x16x32_bf16 v[12:15], v[146:149], v[224:227], v[12:15]
	v_mfma_f32_16x16x32_bf16 v[8:11], v[150:153], v[224:227], v[8:11]
	v_mfma_f32_16x16x32_bf16 v[4:7], v[154:157], v[224:227], v[4:7]
	v_mfma_f32_16x16x32_bf16 v[0:3], v[158:161], v[224:227], v[0:3]
	s_waitcnt lgkmcnt(0)
	v_mfma_f32_16x16x32_bf16 v[12:15], v[204:207], v[228:231], v[12:15]
	v_mfma_f32_16x16x32_bf16 v[8:11], v[208:211], v[228:231], v[8:11]
	v_mfma_f32_16x16x32_bf16 v[4:7], v[212:215], v[228:231], v[4:7]
	v_mfma_f32_16x16x32_bf16 v[0:3], v[216:219], v[228:231], v[0:3]
	s_branch .LBB0_1743
